# P9 row assignment balanced: waves that own a context row (16 partial tiles) take 5 latent rows, their 3 other rows go to the 3 neighbouring waves
# speedup vs baseline: 1.0013x; 1.0013x over previous
; #define GAS __attribute__((address_space(1)))
;     ...
;     bf16* XN = (bf16*)(F.ws + WS_XN);
;     const int gw = F.vcu * NWAVES + F.wave, NGW = F.G * NWAVES;
;     for (int m = gw; m < nrows; m += NGW) {
;         const float* xrow = m < ML ? src_lat + (size_t)m * DM : src_ctx + (size_t)(m - ML) * DM;
;         const int cnd = m < SEQ ? 0 : (m < ML ? 1 : 2);
;         const GAS f32x4* xr = (const GAS f32x4*)xrow + F.lane;
;         f32x4 v[4]; float s = 0.f;
;         if (lat_bf16 && m < ML) {
.LBB0_158:
	s_or_b64 exec, exec, s[0:1]
	v_readlane_b32 s0, v243, 20
	s_lshl_b32 s0, s0, 3
	v_readlane_b32 s1, v243, 24
	s_add_i32 s0, s0, s1
	s_cmpk_gt_i32 s0, 0x41ff
	s_waitcnt lgkmcnt(0)
	s_barrier
	s_cbranch_scc1 .LBB0_178
	v_readlane_b32 s1, v243, 18
	s_lshl_b32 s6, s1, 3
	v_lshlrev_b32_e32 v0, 4, v172
	s_add_u32 s16, s80, 0xd900000
	s_waitcnt vmcnt(35)
	v_add_u32_e32 v102, 0, v0
	v_readlane_b32 s4, v243, 22
	s_addc_u32 s17, s81, 0
	s_waitcnt vmcnt(0)
	ds_read_b128 v[2:5], v102
	ds_read_b128 v[6:9], v102 offset:1024
	ds_read_b128 v[10:13], v102 offset:2048
	ds_read_b128 v[14:17], v102 offset:3072
	v_readlane_b32 s5, v243, 23
	s_ashr_i32 s1, s0, 31
	v_lshlrev_b32_e32 v84, 3, v172
	v_lshl_add_u64 v[82:83], s[4:5], 0, v[0:1]
	s_lshl_b64 s[4:5], s[0:1], 11
	s_add_u32 s8, s80, s4
	s_addc_u32 s9, s81, s5
	s_ashr_i32 s7, s6, 31
	s_lshl_b64 s[10:11], s[6:7], 11
	s_add_u32 s12, s44, s4
	v_mov_b32_e32 v85, v1
	s_addc_u32 s13, s45, s5
	v_lshlrev_b32_e32 v0, 4, v172
	s_mov_b32 s32, s0
	s_cmpk_lt_i32 s0, 0x4000
	s_cbranch_scc0 .Ln3a_nopre
	v_lshl_add_u64 v[228:229], s[12:13], 0, v[84:85]
	global_load_dwordx2 v[220:221], v[228:229], off
	global_load_dwordx2 v[222:223], v[228:229], off offset:512
	global_load_dwordx2 v[224:225], v[228:229], off offset:1024
	global_load_dwordx2 v[226:227], v[228:229], off offset:1536
	s_waitcnt vmcnt(0)

; #define GAS __attribute__((address_space(1)))
;     ...
;     for (int m = gw; m < nrows; m += NGW) {
;         const float* xrow = m < ML ? src_lat + (size_t)m * DM : src_ctx + (size_t)(m - ML) * DM;
;         const int cnd = m < SEQ ? 0 : (m < ML ? 1 : 2);
;         const GAS f32x4* xr = (const GAS f32x4*)xrow + F.lane;
;         f32x4 v[4]; float s = 0.f;
;         if (lat_bf16 && m < ML) {
;     ...
;         for (int j = 0; j < 4; ++j) s += (v[j].x * v[j].x + v[j].y * v[j].y) + (v[j].z * v[j].z + v[j].w * v[j].w);
;         const float rstd = 1.f / sqrtf(wave_sum(s, F.lane) * (1.f / DM) + NORM_EPS);
.LBB0_160:
	v_pk_mul_f32 v[38:39], v[32:33], v[32:33]
	v_pk_mul_f32 v[40:41], v[30:31], v[30:31]
	v_pk_mul_f32 v[34:35], v[28:29], v[28:29]
	v_pk_mul_f32 v[36:37], v[26:27], v[26:27]
	v_pk_mov_b32 v[42:43], v[40:41], v[38:39] op_sel:[1,0]
	v_mov_b32_e32 v41, v39
	v_pk_add_f32 v[38:39], v[42:43], v[40:41]
	v_pk_mov_b32 v[40:41], v[36:37], v[34:35] op_sel:[1,0]
	v_mov_b32_e32 v37, v35
	v_pk_add_f32 v[34:35], v[40:41], v[36:37]
	v_pk_add_f32 v[38:39], v[38:39], v[38:39] op_sel_hi:[0,1]
	v_pk_add_f32 v[34:35], v[34:35], v[34:35] op_sel_hi:[0,1]
	v_mul_f32_e32 v34, v22, v22
	v_pk_fma_f32 v[36:37], v[22:23], v[22:23], v[34:35] op_sel_hi:[1,1,0]
	v_mul_f32_e32 v34, v24, v24
	v_pk_fma_f32 v[40:41], v[24:25], v[24:25], v[34:35] op_sel_hi:[1,1,0]
	v_mul_f32_e32 v36, v18, v18
	v_mul_f32_e32 v40, v19, v19
	v_mul_f32_e32 v38, v20, v20
	v_mul_f32_e32 v34, v21, v21
	v_pk_add_f32 v[36:37], v[36:37], v[40:41]
	v_pk_add_f32 v[34:35], v[38:39], v[34:35]
	s_and_b64 s[4:5], exec, s[4:5]
	v_pk_add_f32 v[34:35], v[36:37], v[34:35]
	s_movk_i32 s1, 0x800
	v_add_f32_e32 v34, v34, v35
	s_cselect_b32 s1, 0x400, s1
	s_cmpk_gt_i32 s0, 0x1fff
	v_add_f32_dpp v34, v34, v34 row_ror:8 row_mask:0xf bank_mask:0xf bound_ctrl:1
	s_cselect_b32 s1, s1, 0
	v_lshl_add_u64 v[44:45], s[8:9], 0, v[84:85]
	v_add_f32_dpp v34, v34, v34 row_ror:4 row_mask:0xf bank_mask:0xf bound_ctrl:1
	s_add_i32 s0, s0, s6
	s_add_u32 s8, s8, s10
	v_add_f32_dpp v34, v34, v34 row_ror:2 row_mask:0xf bank_mask:0xf bound_ctrl:1
	s_addc_u32 s9, s9, s11
	s_add_u32 s12, s12, s10
	v_add_f32_dpp v34, v34, v34 row_ror:1 row_mask:0xf bank_mask:0xf bound_ctrl:1
	s_addc_u32 s13, s13, s11
	s_bitcmp1_b32 s32, 31
	s_cbranch_scc1 .Lbal_exit
	s_and_b32 s98, s32, 3
	s_sub_i32 s99, s0, s32
	s_cmp_lg_u32 s98, 0
	s_cbranch_scc1 .Lbal_r
	s_cmpk_lg_u32 s99, 0x2800
	s_cbranch_scc1 .Lbal_done
	s_lshr_b32 s99, s32, 2
	s_add_i32 s99, s99, 0x4000
	s_branch .Lbal_jump
.Lbal_r:
	s_cmpk_lg_u32 s99, 0x4000
	s_cbranch_scc1 .Lbal_done
	s_add_i32 s99, s98, 4
	s_lshl_b32 s99, s99, 11
	s_add_i32 s99, s99, s32
	s_sub_i32 s99, s99, s98
.Lbal_jump:
	s_sub_i32 s98, s99, s0
	s_mov_b32 s0, s99
	s_bitset1_b32 s32, 31
	s_lshl_b32 s98, s98, 11
	s_ashr_i32 s99, s98, 31
	s_add_u32 s8, s8, s98
	s_addc_u32 s9, s9, s99
	s_add_u32 s12, s12, s98
	s_addc_u32 s13, s13, s99
	s_branch .Lbal_done
